# adds: down-phase edge-row conv fix-up issues all 14 operand loads of a trip together (was two memory round trips per trip)
# baseline (speedup 1.0000x reference)
.LBB0_578:
	v_add_u32_e32 v2, 0x2bf, v4
	s_movk_i32 s0, 0x57f
	v_cmp_gt_u32_e32 vcc, s0, v2
	s_and_b64 s[0:1], vcc, s[22:23]
	s_xor_b64 s[0:1], s[0:1], -1
	s_and_saveexec_b64 s[30:31], s[0:1]
	s_cbranch_execz .LBB0_577
	v_add_u32_e32 v2, 0xfffffd40, v4
	s_movk_i32 s0, 0x2bf
	v_cmp_lt_u32_e64 s[0:1], s0, v2
	s_or_b64 s[0:1], s[0:1], s[28:29]
	s_and_b64 exec, exec, s[0:1]
	s_cbranch_execz .LBB0_577
	s_mov_b32 s0, 0x2e8ba2e9
	v_mul_hi_i32 v2, v4, s0
	v_lshrrev_b32_e32 v5, 31, v2
	v_ashrrev_i32_e32 v2, 7, v2
	v_add_u32_e32 v2, v2, v5
	s_movk_i32 s0, 0x2c0
	v_mul_lo_u32 v2, v2, s0
	v_sub_u32_e32 v2, v4, v2
	v_lshlrev_b32_e32 v62, 2, v2
	v_cndmask_b32_e64 v7, 0, -1, vcc
	v_cndmask_b32_e32 v6, v202, v204, vcc
	v_cndmask_b32_e64 v2, v205, 0, vcc
	v_ashrrev_i32_e32 v63, 31, v62
	v_lshl_add_u64 v[6:7], s[24:25], 0, v[6:7]
	v_lshl_add_u64 v[10:11], s[24:25], 0, v[2:3]
	v_lshlrev_b64 v[58:59], 2, v[62:63]
	v_lshl_add_u64 v[18:19], v[6:7], 0, v[58:59]
	v_lshl_add_u64 v[22:23], v[10:11], 0, v[58:59]
	v_cndmask_b32_e32 v2, v206, v207, vcc
	v_cndmask_b32_e64 v5, v208, 0, vcc
	global_load_dwordx4 v[6:9], v[18:19], off
	global_load_dwordx4 v[10:13], v[22:23], off
	v_add_co_u32_e32 v18, vcc, s75, v18
	v_lshl_add_u64 v[14:15], s[24:25], 0, v[2:3]
	s_nop 0
	v_addc_co_u32_e32 v19, vcc, 0, v19, vcc
	v_add_co_u32_e32 v22, vcc, s75, v22
	v_lshl_add_u64 v[26:27], v[14:15], 0, v[58:59]
	s_nop 0
	v_addc_co_u32_e32 v23, vcc, 0, v23, vcc
	v_lshl_add_u64 v[30:31], s[2:3], 0, v[58:59]
	v_lshl_add_u64 v[34:35], s[6:7], 0, v[58:59]
	v_lshl_add_u64 v[38:39], s[8:9], 0, v[58:59]
	v_lshl_add_u64 v[42:43], s[10:11], 0, v[58:59]
	v_lshl_add_u64 v[46:47], s[12:13], 0, v[58:59]
	v_lshl_add_u64 v[50:51], s[14:15], 0, v[58:59]
	v_lshl_add_u64 v[54:55], s[4:5], 0, v[58:59]
	v_lshl_add_u64 v[58:59], s[16:17], 0, v[58:59]
	global_load_dwordx4 v[14:17], v[26:27], off
	v_add_co_u32_e32 v26, vcc, s75, v26
	global_load_dwordx4 v[18:21], v[18:19], off offset:3072
	s_nop 0
	v_addc_co_u32_e32 v27, vcc, 0, v27, vcc
	global_load_dwordx4 v[38:41], v[38:39], off
	v_or_b32_e32 v2, s37, v5
	global_load_dwordx4 v[42:45], v[42:43], off
	v_mul_u32_u24_e32 v2, 0xb00, v2
	global_load_dwordx4 v[54:57], v[54:55], off
	v_readlane_b32 s0, v252, 60
	global_load_dwordx4 v[58:61], v[58:59], off
	v_lshlrev_b32_e32 v2, 1, v2
	global_load_dwordx4 v[22:25], v[22:23], off offset:3072
	v_readlane_b32 s1, v252, 61
	global_load_dwordx4 v[46:49], v[46:47], off
	global_load_dwordx4 v[26:29], v[26:27], off offset:3072
	global_load_dwordx4 v[50:53], v[50:51], off
	global_load_dwordx4 v[30:33], v[30:31], off
	global_load_dwordx4 v[34:37], v[34:35], off
	s_waitcnt vmcnt(6)
	v_pk_fma_f32 v[18:19], v[18:19], v[42:43], v[58:59]
	v_lshl_add_u64 v[64:65], s[0:1], 0, v[2:3]
	s_waitcnt vmcnt(4)
	v_pk_fma_f32 v[18:19], v[22:23], v[46:47], v[18:19]
	v_pk_fma_f32 v[20:21], v[20:21], v[44:45], v[60:61]
	v_pk_fma_f32 v[20:21], v[24:25], v[48:49], v[20:21]
	v_lshl_add_u64 v[62:63], v[62:63], 1, v[64:65]
	s_waitcnt vmcnt(2)
	v_pk_fma_f32 v[18:19], v[26:27], v[50:51], v[18:19]
	s_nop 0
	v_mul_f32_e32 v2, 0xbfb8aa3b, v18
	v_exp_f32_e32 v2, v2
	v_pk_fma_f32 v[20:21], v[28:29], v[52:53], v[20:21]
	s_waitcnt vmcnt(1)
	v_pk_fma_f32 v[6:7], v[6:7], v[30:31], v[54:55]
	v_pk_fma_f32 v[8:9], v[8:9], v[32:33], v[56:57]
	v_add_f32_e32 v2, 1.0, v2
	v_rcp_f32_e32 v22, v2
	v_mul_f32_e32 v2, 0xbfb8aa3b, v19
	v_exp_f32_e32 v2, v2
	s_waitcnt vmcnt(0)
	v_pk_fma_f32 v[6:7], v[10:11], v[34:35], v[6:7]
	v_pk_fma_f32 v[8:9], v[12:13], v[36:37], v[8:9]
	v_pk_fma_f32 v[6:7], v[14:15], v[38:39], v[6:7]
	v_add_f32_e32 v2, 1.0, v2
	v_rcp_f32_e32 v23, v2
	v_mul_f32_e32 v2, 0xbfb8aa3b, v20
	v_exp_f32_e32 v2, v2
	v_pk_fma_f32 v[8:9], v[16:17], v[40:41], v[8:9]
	v_pk_mul_f32 v[10:11], v[18:19], v[22:23]
	v_add_f32_e32 v2, 1.0, v2
	v_pk_mul_f32 v[6:7], v[6:7], v[10:11]
	v_rcp_f32_e32 v10, v2
	v_mul_f32_e32 v2, 0xbfb8aa3b, v21
	v_exp_f32_e32 v2, v2
	v_cvt_pk_bf16_f32 v6, v6, v7
	v_add_f32_e32 v2, 1.0, v2
	v_rcp_f32_e32 v11, v2
	s_nop 0
	v_pk_mul_f32 v[10:11], v[20:21], v[10:11]
	s_nop 0
	v_pk_mul_f32 v[8:9], v[8:9], v[10:11]
	s_nop 0
	v_cvt_pk_bf16_f32 v7, v8, v9
	global_store_dwordx2 v[62:63], v[6:7], off
	s_branch .LBB0_577
